# EpiSwiglu GEMMs: three K-iterations before a tile ends each wave touches the tile's row-statistics cache lines (L2 prefetch; probe: rss wait 20 -> 12 us in GU1)
# speedup vs baseline: 1.0090x; 1.0090x over previous
; #define PG8_STAGE(bufoff, gbase, voff) do { _Pragma("unroll") for (int _i = 0; _i < 2; ++_i) \
;         __builtin_amdgcn_global_load_lds((const unsigned*)((const char*)(gbase) + (voff)[_i]), (PG8_LAS unsigned*)(lds + (bufoff) + ldsw + _i * 8192), 16, 0, 0); } while (0)
; #define PG8_LDA(dst, b, h) do { _Pragma("unroll") for (int m = 0; m < 4; ++m) _Pragma("unroll") for (int k = 0; k < 2; ++k) dst[m][k] = *(const PG8_LAS bf16x8*)(lds + PG8_SA(b, h) + aoff + m * 2048 + k * 1024); } while (0)
; #define PG8_LDB(dst, b, h) do { _Pragma("unroll") for (int n = 0; n < 2; ++n) _Pragma("unroll") for (int k = 0; k < 2; ++k) dst[n][k] = *(const PG8_LAS bf16x8*)(lds + PG8_SB(b, h) + boff + n * 2048 + k * 1024); } while (0)
; #define PG8_MMA(ai, bj, At, Bt) do { __builtin_amdgcn_s_setprio(1); _Pragma("unroll") for (int m = 0; m < 4; ++m) _Pragma("unroll") for (int n = 0; n < 2; ++n) _Pragma("unroll") for (int k = 0; k < 2; ++k) \
;         acc[ai][bj][m][n] = __builtin_amdgcn_mfma_f32_16x16x32_bf16(Bt[n][k], At[m][k], acc[ai][bj][m][n], 0, 0, 0); __builtin_amdgcn_s_setprio(0); } while (0)
; #define PG8_WAIT_V(n) asm volatile("s_waitcnt vmcnt(" #n ")" ::: "memory")
; #define PG8_WAIT_L(n) asm volatile("s_waitcnt lgkmcnt(" #n ")" ::: "memory")
; #define PG8_BAR __builtin_amdgcn_s_barrier()
; #define PG8_SCHED __builtin_amdgcn_sched_barrier(0)
; template <class Epi, class Sched, bool ALIGN_EPI = false, bool SP2 = false>
; __device__ __forceinline__ void gemm_phase(PG8_LAS unsigned char* lds, const Gemm g, const Sched& S, const Epi& E) {
;     ...
;             PG8_LDB(B0, 0, 0); PG8_LDB(B1, 0, 1); PG8_SCHED; PG8_LDA(At, 0, 0); PG8_STAGE(PG8_SA(1, 1), a1 + hstep, voffA);
;             PG8_WAIT_V(8); PG8_WAIT_L(0); PG8_BAR; PG8_MMA(0, 0, At, B0); PG8_MMA(0, 1, At, B1); PG8_BAR; PG8_SCHED;
;             PG8_LDA(At, 0, 1); PG8_STAGE(PG8_SB(0, 0), b2, voffB); PG8_STAGE(PG8_SB(0, 1), b2 + hstep, voffB); PG8_STAGE(PG8_SA(0, 0), a2, voffA);
;             PG8_WAIT_V(8); PG8_WAIT_L(0); PG8_BAR; PG8_MMA(1, 0, At, B0); PG8_MMA(1, 1, At, B1); PG8_BAR; PG8_SCHED;
.LBB0_318:
	s_add_i32 s60, s59, 2
	s_add_u32 s61, s80, 0x80
	s_addc_u32 s62, s81, 0
	s_add_i32 s82, 0, 0x10000
	s_cmp_eq_u32 s51, s59
	s_cselect_b32 s71, s43, s62
	s_cselect_b32 s70, s42, s61
	v_add_u32_e32 v144, s82, v149
	s_cselect_b32 s63, s79, s58
	s_cselect_b32 s62, s78, s57
	s_add_i32 s59, 0, 0x14000
	ds_read_b128 v[140:143], v144
	ds_read_b128 v[168:171], v144 offset:1024
	ds_read_b128 v[172:175], v144 offset:2048
	ds_read_b128 v[176:179], v144 offset:3072
	v_add_u32_e32 v144, s59, v149
	ds_read_b128 v[180:183], v144
	ds_read_b128 v[184:187], v144 offset:1024
	ds_read_b128 v[188:191], v144 offset:2048
	ds_read_b128 v[192:195], v144 offset:3072
	v_lshl_add_u64 v[144:145], s[80:81], 0, v[136:137]
	s_add_i32 m0, s31, 0xc000
	ds_read_b128 v[196:199], v157
	ds_read_b128 v[200:203], v157 offset:1024
	ds_read_b128 v[204:207], v157 offset:2048
	ds_read_b128 v[210:213], v157 offset:3072
	ds_read_b128 v[214:217], v157 offset:4096
	ds_read_b128 v[218:221], v157 offset:5120
	ds_read_b128 v[222:225], v157 offset:6144
	ds_read_b128 v[238:241], v157 offset:7168
	global_load_lds_dwordx4 v[144:145], off
	v_lshl_add_u64 v[144:145], s[80:81], 0, v[138:139]
	s_add_i32 m0, s31, 0xe000
	s_nop 0
	global_load_lds_dwordx4 v[144:145], off
	s_waitcnt vmcnt(8)
	s_waitcnt lgkmcnt(0)
	s_barrier
	s_setprio 1
	s_waitcnt lgkmcnt(0)
	v_mfma_f32_16x16x32_bf16 v[122:125], v[140:143], v[196:199], v[122:125]
	v_mfma_f32_16x16x32_bf16 v[114:117], v[172:175], v[196:199], v[114:117]
	v_mfma_f32_16x16x32_bf16 v[106:109], v[140:143], v[204:207], v[106:109]
	v_mfma_f32_16x16x32_bf16 v[98:101], v[172:175], v[204:207], v[98:101]
	v_mfma_f32_16x16x32_bf16 v[90:93], v[140:143], v[214:217], v[90:93]
	v_mfma_f32_16x16x32_bf16 v[82:85], v[172:175], v[214:217], v[82:85]
	v_mfma_f32_16x16x32_bf16 v[74:77], v[140:143], v[222:225], v[74:77]
	v_mfma_f32_16x16x32_bf16 v[66:69], v[172:175], v[222:225], v[66:69]
	v_mfma_f32_16x16x32_bf16 v[122:125], v[168:171], v[200:203], v[122:125]
	v_mfma_f32_16x16x32_bf16 v[114:117], v[176:179], v[200:203], v[114:117]
	v_mfma_f32_16x16x32_bf16 v[106:109], v[168:171], v[210:213], v[106:109]
	v_mfma_f32_16x16x32_bf16 v[98:101], v[176:179], v[210:213], v[98:101]
	v_mfma_f32_16x16x32_bf16 v[90:93], v[168:171], v[218:221], v[90:93]
	v_mfma_f32_16x16x32_bf16 v[82:85], v[176:179], v[218:221], v[82:85]
	v_mfma_f32_16x16x32_bf16 v[74:77], v[168:171], v[238:241], v[74:77]
	v_mfma_f32_16x16x32_bf16 v[66:69], v[176:179], v[238:241], v[66:69]
	s_setprio 0
	s_setprio 1
	v_mfma_f32_16x16x32_bf16 v[126:129], v[180:183], v[196:199], v[126:129]
	v_mfma_f32_16x16x32_bf16 v[118:121], v[188:191], v[196:199], v[118:121]
	v_mfma_f32_16x16x32_bf16 v[110:113], v[180:183], v[204:207], v[110:113]
	v_mfma_f32_16x16x32_bf16 v[102:105], v[188:191], v[204:207], v[102:105]
	v_mfma_f32_16x16x32_bf16 v[94:97], v[180:183], v[214:217], v[94:97]
	v_mfma_f32_16x16x32_bf16 v[86:89], v[188:191], v[214:217], v[86:89]
	v_mfma_f32_16x16x32_bf16 v[78:81], v[180:183], v[222:225], v[78:81]
	v_mfma_f32_16x16x32_bf16 v[70:73], v[188:191], v[222:225], v[70:73]
	v_mfma_f32_16x16x32_bf16 v[126:129], v[184:187], v[200:203], v[126:129]
	v_mfma_f32_16x16x32_bf16 v[118:121], v[192:195], v[200:203], v[118:121]
	v_mfma_f32_16x16x32_bf16 v[110:113], v[184:187], v[210:213], v[110:113]
	v_mfma_f32_16x16x32_bf16 v[102:105], v[192:195], v[210:213], v[102:105]
	v_mfma_f32_16x16x32_bf16 v[94:97], v[184:187], v[218:221], v[94:97]
	v_mfma_f32_16x16x32_bf16 v[86:89], v[192:195], v[218:221], v[86:89]
	v_mfma_f32_16x16x32_bf16 v[78:81], v[184:187], v[238:241], v[78:81]
	v_mfma_f32_16x16x32_bf16 v[70:73], v[192:195], v[238:241], v[70:73]
	s_setprio 0
	s_barrier
	s_add_i32 s61, s82, s0
	v_lshl_add_u64 v[144:145], s[62:63], 0, v[0:1]
	s_mov_b32 m0, s61
	ds_read_b128 v[196:199], v157 offset:16384
	ds_read_b128 v[200:203], v157 offset:17408
	ds_read_b128 v[204:207], v157 offset:18432
	ds_read_b128 v[210:213], v157 offset:19456
	ds_read_b128 v[214:217], v157 offset:20480
	ds_read_b128 v[218:221], v157 offset:21504
	ds_read_b128 v[222:225], v157 offset:22528
	ds_read_b128 v[238:241], v157 offset:23552
	global_load_lds_dwordx4 v[144:145], off
	s_add_i32 m0, s61, 0x2000
	v_lshl_add_u64 v[150:151], s[62:63], 0, v[130:131]
	s_add_u32 s62, s62, s18
	s_addc_u32 s63, s63, s19
	s_add_i32 s59, s59, s0
	global_load_lds_dwordx4 v[150:151], off
	v_lshl_add_u64 v[154:155], s[62:63], 0, v[0:1]
	s_mov_b32 m0, s59
	v_lshl_add_u64 v[226:227], s[62:63], 0, v[130:131]
	global_load_lds_dwordx4 v[154:155], off
	s_add_i32 m0, s59, 0x2000
	v_lshl_add_u64 v[242:243], s[70:71], 0, v[134:135]
	global_load_lds_dwordx4 v[226:227], off
	s_mov_b32 m0, s31
	v_lshl_add_u64 v[244:245], s[70:71], 0, v[132:133]
	global_load_lds_dwordx4 v[242:243], off
	s_mov_b32 m0, s33
	s_nop 0
	global_load_lds_dwordx4 v[244:245], off
	s_waitcnt vmcnt(8)
	s_waitcnt lgkmcnt(0)
	s_barrier
; #define PG8_STAGE(bufoff, gbase, voff) do { _Pragma("unroll") for (int _i = 0; _i < 2; ++_i) \
;         __builtin_amdgcn_global_load_lds((const unsigned*)((const char*)(gbase) + (voff)[_i]), (PG8_LAS unsigned*)(lds + (bufoff) + ldsw + _i * 8192), 16, 0, 0); } while (0)
; #define PG8_LDA(dst, b, h) do { _Pragma("unroll") for (int m = 0; m < 4; ++m) _Pragma("unroll") for (int k = 0; k < 2; ++k) dst[m][k] = *(const PG8_LAS bf16x8*)(lds + PG8_SA(b, h) + aoff + m * 2048 + k * 1024); } while (0)
; #define PG8_LDB(dst, b, h) do { _Pragma("unroll") for (int n = 0; n < 2; ++n) _Pragma("unroll") for (int k = 0; k < 2; ++k) dst[n][k] = *(const PG8_LAS bf16x8*)(lds + PG8_SB(b, h) + boff + n * 2048 + k * 1024); } while (0)
; #define PG8_MMA(ai, bj, At, Bt) do { __builtin_amdgcn_s_setprio(1); _Pragma("unroll") for (int m = 0; m < 4; ++m) _Pragma("unroll") for (int n = 0; n < 2; ++n) _Pragma("unroll") for (int k = 0; k < 2; ++k) \
;         acc[ai][bj][m][n] = __builtin_amdgcn_mfma_f32_16x16x32_bf16(Bt[n][k], At[m][k], acc[ai][bj][m][n], 0, 0, 0); __builtin_amdgcn_s_setprio(0); } while (0)
; #define PG8_WAIT_V(n) asm volatile("s_waitcnt vmcnt(" #n ")" ::: "memory")
; #define PG8_WAIT_L(n) asm volatile("s_waitcnt lgkmcnt(" #n ")" ::: "memory")
; #define PG8_BAR __builtin_amdgcn_s_barrier()
; #define PG8_SCHED __builtin_amdgcn_sched_barrier(0)
; template <class Epi, class Sched, bool ALIGN_EPI = false, bool SP2 = false>
; __device__ __forceinline__ void gemm_phase(PG8_LAS unsigned char* lds, const Gemm g, const Sched& S, const Epi& E) {
;     ...
;             PG8_WAIT_V(8); PG8_WAIT_L(0); PG8_BAR; PG8_MMA(1, 0, At, B0); PG8_MMA(1, 1, At, B1); PG8_BAR; PG8_SCHED;
;             PG8_LDB(B0, 1, 0); PG8_LDB(B1, 1, 1); PG8_SCHED; PG8_LDA(At, 1, 0); PG8_STAGE(PG8_SA(0, 1), a2 + hstep, voffA);
;             PG8_WAIT_V(8); PG8_WAIT_L(0); PG8_BAR; PG8_MMA(0, 0, At, B0); PG8_MMA(0, 1, At, B1); PG8_BAR; PG8_SCHED;
	s_setprio 1
	s_waitcnt lgkmcnt(0)
	v_mfma_f32_16x16x32_bf16 v[58:61], v[140:143], v[196:199], v[58:61]
	v_mfma_f32_16x16x32_bf16 v[50:53], v[172:175], v[196:199], v[50:53]
	v_mfma_f32_16x16x32_bf16 v[42:45], v[140:143], v[204:207], v[42:45]
	v_mfma_f32_16x16x32_bf16 v[34:37], v[172:175], v[204:207], v[34:37]
	v_mfma_f32_16x16x32_bf16 v[26:29], v[140:143], v[214:217], v[26:29]
	v_mfma_f32_16x16x32_bf16 v[18:21], v[172:175], v[214:217], v[18:21]
	v_mfma_f32_16x16x32_bf16 v[10:13], v[140:143], v[222:225], v[10:13]
	v_mfma_f32_16x16x32_bf16 v[6:9], v[172:175], v[222:225], v[6:9]
	v_mfma_f32_16x16x32_bf16 v[58:61], v[168:171], v[200:203], v[58:61]
	v_mfma_f32_16x16x32_bf16 v[50:53], v[176:179], v[200:203], v[50:53]
	v_mfma_f32_16x16x32_bf16 v[42:45], v[168:171], v[210:213], v[42:45]
	v_mfma_f32_16x16x32_bf16 v[34:37], v[176:179], v[210:213], v[34:37]
	v_mfma_f32_16x16x32_bf16 v[26:29], v[168:171], v[218:221], v[26:29]
	v_mfma_f32_16x16x32_bf16 v[18:21], v[176:179], v[218:221], v[18:21]
	v_mfma_f32_16x16x32_bf16 v[10:13], v[168:171], v[238:241], v[10:13]
	v_mfma_f32_16x16x32_bf16 v[6:9], v[176:179], v[238:241], v[6:9]
	s_setprio 0
	s_setprio 1
	v_mfma_f32_16x16x32_bf16 v[62:65], v[180:183], v[196:199], v[62:65]
	v_mfma_f32_16x16x32_bf16 v[54:57], v[188:191], v[196:199], v[54:57]
	v_mfma_f32_16x16x32_bf16 v[46:49], v[180:183], v[204:207], v[46:49]
	v_mfma_f32_16x16x32_bf16 v[38:41], v[188:191], v[204:207], v[38:41]
	v_mfma_f32_16x16x32_bf16 v[30:33], v[180:183], v[214:217], v[30:33]
	v_mfma_f32_16x16x32_bf16 v[22:25], v[188:191], v[214:217], v[22:25]
	v_mfma_f32_16x16x32_bf16 v[14:17], v[180:183], v[222:225], v[14:17]
	v_mfma_f32_16x16x32_bf16 v[2:5], v[188:191], v[222:225], v[2:5]
	v_mfma_f32_16x16x32_bf16 v[62:65], v[184:187], v[200:203], v[62:65]
	v_mfma_f32_16x16x32_bf16 v[54:57], v[192:195], v[200:203], v[54:57]
	v_mfma_f32_16x16x32_bf16 v[46:49], v[184:187], v[210:213], v[46:49]
	v_mfma_f32_16x16x32_bf16 v[38:41], v[192:195], v[210:213], v[38:41]
	v_mfma_f32_16x16x32_bf16 v[30:33], v[184:187], v[218:221], v[30:33]
	v_mfma_f32_16x16x32_bf16 v[22:25], v[192:195], v[218:221], v[22:25]
	v_mfma_f32_16x16x32_bf16 v[14:17], v[184:187], v[238:241], v[14:17]
	v_mfma_f32_16x16x32_bf16 v[2:5], v[192:195], v[238:241], v[2:5]
	s_setprio 0
	s_barrier
	s_add_i32 s59, 0, 0x18000
	v_add_u32_e32 v146, s59, v149
	s_add_i32 s61, 0, 0x1c000
	ds_read_b128 v[140:143], v146
	ds_read_b128 v[168:171], v146 offset:1024
	ds_read_b128 v[172:175], v146 offset:2048
	ds_read_b128 v[176:179], v146 offset:3072
	v_add_u32_e32 v146, s61, v149
	ds_read_b128 v[180:183], v146
	ds_read_b128 v[184:187], v146 offset:1024
	ds_read_b128 v[188:191], v146 offset:2048
	ds_read_b128 v[192:195], v146 offset:3072
	s_add_u32 s62, s70, s18
	s_addc_u32 s63, s71, s19
	s_mov_b32 m0, s34
	v_lshl_add_u64 v[246:247], s[62:63], 0, v[134:135]
	ds_read_b128 v[196:199], v157 offset:32768
	ds_read_b128 v[200:203], v157 offset:33792
	ds_read_b128 v[204:207], v157 offset:34816
	ds_read_b128 v[210:213], v157 offset:35840
	ds_read_b128 v[214:217], v157 offset:36864
	ds_read_b128 v[218:221], v157 offset:37888
	ds_read_b128 v[222:225], v157 offset:38912
	ds_read_b128 v[238:241], v157 offset:39936
	global_load_lds_dwordx4 v[246:247], off
	v_lshl_add_u64 v[246:247], s[62:63], 0, v[132:133]
	s_mov_b32 m0, s35
	s_nop 0
	global_load_lds_dwordx4 v[246:247], off
	s_waitcnt vmcnt(8)
	s_waitcnt lgkmcnt(0)
	s_barrier
	s_setprio 1
	s_waitcnt lgkmcnt(0)
	v_mfma_f32_16x16x32_bf16 v[122:125], v[140:143], v[196:199], v[122:125]
	v_mfma_f32_16x16x32_bf16 v[114:117], v[172:175], v[196:199], v[114:117]
	v_mfma_f32_16x16x32_bf16 v[106:109], v[140:143], v[204:207], v[106:109]
	v_mfma_f32_16x16x32_bf16 v[98:101], v[172:175], v[204:207], v[98:101]
	v_mfma_f32_16x16x32_bf16 v[90:93], v[140:143], v[214:217], v[90:93]
	v_mfma_f32_16x16x32_bf16 v[82:85], v[172:175], v[214:217], v[82:85]
	v_mfma_f32_16x16x32_bf16 v[74:77], v[140:143], v[222:225], v[74:77]
	v_mfma_f32_16x16x32_bf16 v[66:69], v[172:175], v[222:225], v[66:69]
	v_mfma_f32_16x16x32_bf16 v[122:125], v[168:171], v[200:203], v[122:125]
	v_mfma_f32_16x16x32_bf16 v[114:117], v[176:179], v[200:203], v[114:117]
	v_mfma_f32_16x16x32_bf16 v[106:109], v[168:171], v[210:213], v[106:109]
	v_mfma_f32_16x16x32_bf16 v[98:101], v[176:179], v[210:213], v[98:101]
	v_mfma_f32_16x16x32_bf16 v[90:93], v[168:171], v[218:221], v[90:93]
	v_mfma_f32_16x16x32_bf16 v[82:85], v[176:179], v[218:221], v[82:85]
	v_mfma_f32_16x16x32_bf16 v[74:77], v[168:171], v[238:241], v[74:77]
	v_mfma_f32_16x16x32_bf16 v[66:69], v[176:179], v[238:241], v[66:69]
	s_setprio 0
	s_setprio 1
	v_mfma_f32_16x16x32_bf16 v[126:129], v[180:183], v[196:199], v[126:129]
	v_mfma_f32_16x16x32_bf16 v[118:121], v[188:191], v[196:199], v[118:121]
	v_mfma_f32_16x16x32_bf16 v[110:113], v[180:183], v[204:207], v[110:113]
	v_mfma_f32_16x16x32_bf16 v[102:105], v[188:191], v[204:207], v[102:105]
	v_mfma_f32_16x16x32_bf16 v[94:97], v[180:183], v[214:217], v[94:97]
	v_mfma_f32_16x16x32_bf16 v[86:89], v[188:191], v[214:217], v[86:89]
	v_mfma_f32_16x16x32_bf16 v[78:81], v[180:183], v[222:225], v[78:81]
	v_mfma_f32_16x16x32_bf16 v[70:73], v[188:191], v[222:225], v[70:73]
	v_mfma_f32_16x16x32_bf16 v[126:129], v[184:187], v[200:203], v[126:129]
	v_mfma_f32_16x16x32_bf16 v[118:121], v[192:195], v[200:203], v[118:121]
	v_mfma_f32_16x16x32_bf16 v[110:113], v[184:187], v[210:213], v[110:113]
	v_mfma_f32_16x16x32_bf16 v[102:105], v[192:195], v[210:213], v[102:105]
	v_mfma_f32_16x16x32_bf16 v[94:97], v[184:187], v[218:221], v[94:97]
	v_mfma_f32_16x16x32_bf16 v[86:89], v[192:195], v[218:221], v[86:89]
	v_mfma_f32_16x16x32_bf16 v[78:81], v[184:187], v[238:241], v[78:81]
	v_mfma_f32_16x16x32_bf16 v[70:73], v[192:195], v[238:241], v[70:73]
	s_setprio 0
	s_barrier
; #define PG8_STAGE(bufoff, gbase, voff) do { _Pragma("unroll") for (int _i = 0; _i < 2; ++_i) \
;         __builtin_amdgcn_global_load_lds((const unsigned*)((const char*)(gbase) + (voff)[_i]), (PG8_LAS unsigned*)(lds + (bufoff) + ldsw + _i * 8192), 16, 0, 0); } while (0)
; #define PG8_LDA(dst, b, h) do { _Pragma("unroll") for (int m = 0; m < 4; ++m) _Pragma("unroll") for (int k = 0; k < 2; ++k) dst[m][k] = *(const PG8_LAS bf16x8*)(lds + PG8_SA(b, h) + aoff + m * 2048 + k * 1024); } while (0)
; #define PG8_MMA(ai, bj, At, Bt) do { __builtin_amdgcn_s_setprio(1); _Pragma("unroll") for (int m = 0; m < 4; ++m) _Pragma("unroll") for (int n = 0; n < 2; ++n) _Pragma("unroll") for (int k = 0; k < 2; ++k) \
;         acc[ai][bj][m][n] = __builtin_amdgcn_mfma_f32_16x16x32_bf16(Bt[n][k], At[m][k], acc[ai][bj][m][n], 0, 0, 0); __builtin_amdgcn_s_setprio(0); } while (0)
; #define PG8_WAIT_V(n) asm volatile("s_waitcnt vmcnt(" #n ")" ::: "memory")
; #define PG8_WAIT_L(n) asm volatile("s_waitcnt lgkmcnt(" #n ")" ::: "memory")
; #define PG8_BAR __builtin_amdgcn_s_barrier()
; #define PG8_SCHED __builtin_amdgcn_sched_barrier(0)
; template <class Epi, class Sched, bool ALIGN_EPI = false, bool SP2 = false>
; __device__ __forceinline__ void gemm_phase(PG8_LAS unsigned char* lds, const Gemm g, const Sched& S, const Epi& E) {
;     ...
;         for (int t = 0; t < nt; t += 2) {
;             const bool last = (t == nt - 2);
;             const char* a1 = cA + (size_t)(t + 1) * kstep;
;             const char* a2 = last ? nA : cA + (size_t)(t + 2) * kstep; const char* b2 = last ? nB : cB + (size_t)(t + 2) * kstep;
;             const char* a3 = a2 + kstep; const char* b3 = b2 + kstep;
;             if (last && has_next) S.a_ready(nxt);
;     ...
;             PG8_LDA(At, 1, 1); PG8_STAGE(PG8_SB(1, 0), b3, voffB); PG8_STAGE(PG8_SB(1, 1), b3 + hstep, voffB); PG8_STAGE(PG8_SA(1, 0), a3, voffA);
;             PG8_WAIT_V(8); PG8_WAIT_L(0); PG8_BAR; PG8_MMA(1, 0, At, B0); PG8_MMA(1, 1, At, B1); PG8_BAR; PG8_SCHED;
	s_add_i32 s59, s59, s0
	v_lshl_add_u64 v[144:145], v[144:145], 0, s[22:23]
	s_mov_b32 m0, s59
	ds_read_b128 v[196:199], v157 offset:49152
	ds_read_b128 v[200:203], v157 offset:50176
	ds_read_b128 v[204:207], v157 offset:51200
	ds_read_b128 v[210:213], v157 offset:52224
	ds_read_b128 v[214:217], v157 offset:53248
	ds_read_b128 v[218:221], v157 offset:54272
	ds_read_b128 v[222:225], v157 offset:55296
	ds_read_b128 v[238:241], v157 offset:56320
	global_load_lds_dwordx4 v[144:145], off
	v_lshl_add_u64 v[144:145], v[150:151], 0, s[22:23]
	s_add_i32 m0, s59, 0x2000
	s_add_i32 s59, s61, s0
	global_load_lds_dwordx4 v[144:145], off
	v_lshl_add_u64 v[144:145], v[154:155], 0, s[22:23]
	s_mov_b32 m0, s59
	s_nop 0
	global_load_lds_dwordx4 v[144:145], off
	v_lshl_add_u64 v[144:145], v[226:227], 0, s[22:23]
	s_add_i32 m0, s59, 0x2000
	s_nop 0
	global_load_lds_dwordx4 v[144:145], off
	v_lshl_add_u64 v[144:145], v[242:243], 0, s[22:23]
	s_mov_b32 m0, s49
	s_nop 0
	global_load_lds_dwordx4 v[144:145], off
	v_lshl_add_u64 v[144:145], v[244:245], 0, s[22:23]
	s_mov_b32 m0, s50
	s_nop 0
	global_load_lds_dwordx4 v[144:145], off
	s_waitcnt vmcnt(8)
	s_waitcnt lgkmcnt(0)
	s_barrier
	s_setprio 1
	s_waitcnt lgkmcnt(0)
	v_mfma_f32_16x16x32_bf16 v[58:61], v[140:143], v[196:199], v[58:61]
	v_mfma_f32_16x16x32_bf16 v[50:53], v[172:175], v[196:199], v[50:53]
	v_mfma_f32_16x16x32_bf16 v[42:45], v[140:143], v[204:207], v[42:45]
	v_mfma_f32_16x16x32_bf16 v[34:37], v[172:175], v[204:207], v[34:37]
	v_mfma_f32_16x16x32_bf16 v[26:29], v[140:143], v[214:217], v[26:29]
	v_mfma_f32_16x16x32_bf16 v[18:21], v[172:175], v[214:217], v[18:21]
	v_mfma_f32_16x16x32_bf16 v[10:13], v[140:143], v[222:225], v[10:13]
	v_mfma_f32_16x16x32_bf16 v[6:9], v[172:175], v[222:225], v[6:9]
	v_mfma_f32_16x16x32_bf16 v[58:61], v[168:171], v[200:203], v[58:61]
	v_mfma_f32_16x16x32_bf16 v[50:53], v[176:179], v[200:203], v[50:53]
	v_mfma_f32_16x16x32_bf16 v[42:45], v[168:171], v[210:213], v[42:45]
	v_mfma_f32_16x16x32_bf16 v[34:37], v[176:179], v[210:213], v[34:37]
	v_mfma_f32_16x16x32_bf16 v[26:29], v[168:171], v[218:221], v[26:29]
	v_mfma_f32_16x16x32_bf16 v[18:21], v[176:179], v[218:221], v[18:21]
	v_mfma_f32_16x16x32_bf16 v[10:13], v[168:171], v[238:241], v[10:13]
	v_mfma_f32_16x16x32_bf16 v[6:9], v[176:179], v[238:241], v[6:9]
	s_setprio 0
	s_setprio 1
	v_mfma_f32_16x16x32_bf16 v[62:65], v[180:183], v[196:199], v[62:65]
	v_mfma_f32_16x16x32_bf16 v[54:57], v[188:191], v[196:199], v[54:57]
	v_mfma_f32_16x16x32_bf16 v[46:49], v[180:183], v[204:207], v[46:49]
	v_mfma_f32_16x16x32_bf16 v[38:41], v[188:191], v[204:207], v[38:41]
	v_mfma_f32_16x16x32_bf16 v[30:33], v[180:183], v[214:217], v[30:33]
	v_mfma_f32_16x16x32_bf16 v[22:25], v[188:191], v[214:217], v[22:25]
	v_mfma_f32_16x16x32_bf16 v[14:17], v[180:183], v[222:225], v[14:17]
	v_mfma_f32_16x16x32_bf16 v[2:5], v[188:191], v[222:225], v[2:5]
	v_mfma_f32_16x16x32_bf16 v[62:65], v[184:187], v[200:203], v[62:65]
	v_mfma_f32_16x16x32_bf16 v[54:57], v[192:195], v[200:203], v[54:57]
	v_mfma_f32_16x16x32_bf16 v[46:49], v[184:187], v[210:213], v[46:49]
	v_mfma_f32_16x16x32_bf16 v[38:41], v[192:195], v[210:213], v[38:41]
	v_mfma_f32_16x16x32_bf16 v[30:33], v[184:187], v[218:221], v[30:33]
	v_mfma_f32_16x16x32_bf16 v[22:25], v[192:195], v[218:221], v[22:25]
	v_mfma_f32_16x16x32_bf16 v[14:17], v[184:187], v[238:241], v[14:17]
	v_mfma_f32_16x16x32_bf16 v[2:5], v[192:195], v[238:241], v[2:5]
	s_setprio 0
	s_barrier
	s_sub_u32 s100, s48, 6
	s_cmp_eq_u32 s59, s100
	s_cbranch_scc0 .Lrs_gu1
	v_readlane_b32 s100, v250, 28
	v_readlane_b32 s101, v250, 29
	v_and_b32_e32 v255, 63, v158
	v_lshlrev_b32_e32 v255, 6, v255
	v_lshl_add_u32 v254, s56, 12, v255
	s_nop 2
	global_load_dword v254, v254, s[100:101]
.Lrs_gu1:
	s_add_u32 s80, s80, 0x100
	s_addc_u32 s81, s81, 0
	s_add_u32 s57, s57, 0x100
	s_addc_u32 s58, s58, 0
	s_cmp_ge_i32 s60, s48
	s_mov_b32 s59, s60
	s_cbranch_scc0 .LBB0_318
	v_readlane_b32 s62, v250, 20
	v_readlane_b32 s82, v250, 19
	s_mov_b32 s84, s62
	v_readlane_b32 s63, v250, 21

; #define PG8_STAGE(bufoff, gbase, voff) do { _Pragma("unroll") for (int _i = 0; _i < 2; ++_i) \
;         __builtin_amdgcn_global_load_lds((const unsigned*)((const char*)(gbase) + (voff)[_i]), (PG8_LAS unsigned*)(lds + (bufoff) + ldsw + _i * 8192), 16, 0, 0); } while (0)
; #define PG8_LDA(dst, b, h) do { _Pragma("unroll") for (int m = 0; m < 4; ++m) _Pragma("unroll") for (int k = 0; k < 2; ++k) dst[m][k] = *(const PG8_LAS bf16x8*)(lds + PG8_SA(b, h) + aoff + m * 2048 + k * 1024); } while (0)
; #define PG8_LDB(dst, b, h) do { _Pragma("unroll") for (int n = 0; n < 2; ++n) _Pragma("unroll") for (int k = 0; k < 2; ++k) dst[n][k] = *(const PG8_LAS bf16x8*)(lds + PG8_SB(b, h) + boff + n * 2048 + k * 1024); } while (0)
; #define PG8_MMA(ai, bj, At, Bt) do { __builtin_amdgcn_s_setprio(1); _Pragma("unroll") for (int m = 0; m < 4; ++m) _Pragma("unroll") for (int n = 0; n < 2; ++n) _Pragma("unroll") for (int k = 0; k < 2; ++k) \
;         acc[ai][bj][m][n] = __builtin_amdgcn_mfma_f32_16x16x32_bf16(Bt[n][k], At[m][k], acc[ai][bj][m][n], 0, 0, 0); __builtin_amdgcn_s_setprio(0); } while (0)
; #define PG8_WAIT_V(n) asm volatile("s_waitcnt vmcnt(" #n ")" ::: "memory")
; #define PG8_WAIT_L(n) asm volatile("s_waitcnt lgkmcnt(" #n ")" ::: "memory")
; #define PG8_BAR __builtin_amdgcn_s_barrier()
; #define PG8_SCHED __builtin_amdgcn_sched_barrier(0)
; template <class Epi, class Sched, bool ALIGN_EPI = false, bool SP2 = false>
; __device__ __forceinline__ void gemm_phase(PG8_LAS unsigned char* lds, const Gemm g, const Sched& S, const Epi& E) {
;     ...
;             PG8_LDB(B0, 0, 0); PG8_LDB(B1, 0, 1); PG8_SCHED; PG8_LDA(At, 0, 0); PG8_STAGE(PG8_SA(1, 1), a1 + hstep, voffA);
;             PG8_WAIT_V(8); PG8_WAIT_L(0); PG8_BAR; PG8_MMA(0, 0, At, B0); PG8_MMA(0, 1, At, B1); PG8_BAR; PG8_SCHED;
;             PG8_LDA(At, 0, 1); PG8_STAGE(PG8_SB(0, 0), b2, voffB); PG8_STAGE(PG8_SB(0, 1), b2 + hstep, voffB); PG8_STAGE(PG8_SA(0, 0), a2, voffA);
;             PG8_WAIT_V(8); PG8_WAIT_L(0); PG8_BAR; PG8_MMA(1, 0, At, B0); PG8_MMA(1, 1, At, B1); PG8_BAR; PG8_SCHED;
.LBB0_1191:
	s_add_i32 s62, s61, 2
	s_add_u32 s63, s68, 0x80
	s_addc_u32 s70, s69, 0
	s_add_i32 s80, 0, 0x10000
	s_cmp_eq_u32 s53, s61
	s_cselect_b32 s71, s43, s70
	s_cselect_b32 s70, s42, s63
	v_add_u32_e32 v144, s80, v149
	s_cselect_b32 s79, s45, s60
	s_cselect_b32 s78, s44, s59
	s_add_i32 s61, 0, 0x14000
	ds_read_b128 v[140:143], v144
	ds_read_b128 v[166:169], v144 offset:1024
	ds_read_b128 v[170:173], v144 offset:2048
	ds_read_b128 v[174:177], v144 offset:3072
	v_add_u32_e32 v144, s61, v149
	ds_read_b128 v[178:181], v144
	ds_read_b128 v[182:185], v144 offset:1024
	ds_read_b128 v[186:189], v144 offset:2048
	ds_read_b128 v[190:193], v144 offset:3072
	v_lshl_add_u64 v[144:145], s[68:69], 0, v[136:137]
	s_add_i32 m0, s34, 0xc000
	ds_read_b128 v[194:197], v157
	ds_read_b128 v[198:201], v157 offset:1024
	ds_read_b128 v[202:205], v157 offset:2048
	ds_read_b128 v[210:213], v157 offset:3072
	ds_read_b128 v[214:217], v157 offset:4096
	ds_read_b128 v[218:221], v157 offset:5120
	ds_read_b128 v[222:225], v157 offset:6144
	ds_read_b128 v[238:241], v157 offset:7168
	global_load_lds_dwordx4 v[144:145], off
	v_lshl_add_u64 v[144:145], s[68:69], 0, v[138:139]
	s_add_i32 m0, s34, 0xe000
	s_nop 0
	global_load_lds_dwordx4 v[144:145], off
	s_waitcnt vmcnt(8)
	s_waitcnt lgkmcnt(0)
	s_barrier
	s_setprio 1
	s_waitcnt lgkmcnt(0)
	v_mfma_f32_16x16x32_bf16 v[122:125], v[140:143], v[194:197], v[122:125]
	v_mfma_f32_16x16x32_bf16 v[114:117], v[170:173], v[194:197], v[114:117]
	v_mfma_f32_16x16x32_bf16 v[106:109], v[140:143], v[202:205], v[106:109]
	v_mfma_f32_16x16x32_bf16 v[98:101], v[170:173], v[202:205], v[98:101]
	v_mfma_f32_16x16x32_bf16 v[90:93], v[140:143], v[214:217], v[90:93]
	v_mfma_f32_16x16x32_bf16 v[82:85], v[170:173], v[214:217], v[82:85]
	v_mfma_f32_16x16x32_bf16 v[74:77], v[140:143], v[222:225], v[74:77]
	v_mfma_f32_16x16x32_bf16 v[66:69], v[170:173], v[222:225], v[66:69]
	v_mfma_f32_16x16x32_bf16 v[122:125], v[166:169], v[198:201], v[122:125]
	v_mfma_f32_16x16x32_bf16 v[114:117], v[174:177], v[198:201], v[114:117]
	v_mfma_f32_16x16x32_bf16 v[106:109], v[166:169], v[210:213], v[106:109]
	v_mfma_f32_16x16x32_bf16 v[98:101], v[174:177], v[210:213], v[98:101]
	v_mfma_f32_16x16x32_bf16 v[90:93], v[166:169], v[218:221], v[90:93]
	v_mfma_f32_16x16x32_bf16 v[82:85], v[174:177], v[218:221], v[82:85]
	v_mfma_f32_16x16x32_bf16 v[74:77], v[166:169], v[238:241], v[74:77]
	v_mfma_f32_16x16x32_bf16 v[66:69], v[174:177], v[238:241], v[66:69]
	s_setprio 0
	s_setprio 1
	v_mfma_f32_16x16x32_bf16 v[126:129], v[178:181], v[194:197], v[126:129]
	v_mfma_f32_16x16x32_bf16 v[118:121], v[186:189], v[194:197], v[118:121]
	v_mfma_f32_16x16x32_bf16 v[110:113], v[178:181], v[202:205], v[110:113]
	v_mfma_f32_16x16x32_bf16 v[102:105], v[186:189], v[202:205], v[102:105]
	v_mfma_f32_16x16x32_bf16 v[94:97], v[178:181], v[214:217], v[94:97]
	v_mfma_f32_16x16x32_bf16 v[86:89], v[186:189], v[214:217], v[86:89]
	v_mfma_f32_16x16x32_bf16 v[78:81], v[178:181], v[222:225], v[78:81]
	v_mfma_f32_16x16x32_bf16 v[70:73], v[186:189], v[222:225], v[70:73]
	v_mfma_f32_16x16x32_bf16 v[126:129], v[182:185], v[198:201], v[126:129]
	v_mfma_f32_16x16x32_bf16 v[118:121], v[190:193], v[198:201], v[118:121]
	v_mfma_f32_16x16x32_bf16 v[110:113], v[182:185], v[210:213], v[110:113]
	v_mfma_f32_16x16x32_bf16 v[102:105], v[190:193], v[210:213], v[102:105]
	v_mfma_f32_16x16x32_bf16 v[94:97], v[182:185], v[218:221], v[94:97]
	v_mfma_f32_16x16x32_bf16 v[86:89], v[190:193], v[218:221], v[86:89]
	v_mfma_f32_16x16x32_bf16 v[78:81], v[182:185], v[238:241], v[78:81]
	v_mfma_f32_16x16x32_bf16 v[70:73], v[190:193], v[238:241], v[70:73]
	s_setprio 0
	s_barrier
	s_add_i32 s63, s80, s6
	v_lshl_add_u64 v[144:145], s[78:79], 0, v[0:1]
	s_mov_b32 m0, s63
	ds_read_b128 v[194:197], v157 offset:16384
	ds_read_b128 v[198:201], v157 offset:17408
	ds_read_b128 v[202:205], v157 offset:18432
	ds_read_b128 v[210:213], v157 offset:19456
	ds_read_b128 v[214:217], v157 offset:20480
	ds_read_b128 v[218:221], v157 offset:21504
	ds_read_b128 v[222:225], v157 offset:22528
	ds_read_b128 v[238:241], v157 offset:23552
	global_load_lds_dwordx4 v[144:145], off
	s_add_i32 m0, s63, 0x2000
	v_lshl_add_u64 v[150:151], s[78:79], 0, v[130:131]
	s_add_u32 s78, s78, s12
	s_addc_u32 s79, s79, s13
	s_add_i32 s61, s61, s6
	global_load_lds_dwordx4 v[150:151], off
	v_lshl_add_u64 v[154:155], s[78:79], 0, v[0:1]
	s_mov_b32 m0, s61
	v_lshl_add_u64 v[206:207], s[78:79], 0, v[130:131]
	global_load_lds_dwordx4 v[154:155], off
	s_add_i32 m0, s61, 0x2000
	v_lshl_add_u64 v[226:227], s[70:71], 0, v[134:135]
	global_load_lds_dwordx4 v[206:207], off
	s_mov_b32 m0, s34
	v_lshl_add_u64 v[242:243], s[70:71], 0, v[132:133]
	global_load_lds_dwordx4 v[226:227], off
	s_mov_b32 m0, s35
	s_nop 0
	global_load_lds_dwordx4 v[242:243], off
	s_waitcnt vmcnt(8)
	s_waitcnt lgkmcnt(0)
	s_barrier
; #define PG8_STAGE(bufoff, gbase, voff) do { _Pragma("unroll") for (int _i = 0; _i < 2; ++_i) \
;         __builtin_amdgcn_global_load_lds((const unsigned*)((const char*)(gbase) + (voff)[_i]), (PG8_LAS unsigned*)(lds + (bufoff) + ldsw + _i * 8192), 16, 0, 0); } while (0)
; #define PG8_LDA(dst, b, h) do { _Pragma("unroll") for (int m = 0; m < 4; ++m) _Pragma("unroll") for (int k = 0; k < 2; ++k) dst[m][k] = *(const PG8_LAS bf16x8*)(lds + PG8_SA(b, h) + aoff + m * 2048 + k * 1024); } while (0)
; #define PG8_LDB(dst, b, h) do { _Pragma("unroll") for (int n = 0; n < 2; ++n) _Pragma("unroll") for (int k = 0; k < 2; ++k) dst[n][k] = *(const PG8_LAS bf16x8*)(lds + PG8_SB(b, h) + boff + n * 2048 + k * 1024); } while (0)
; #define PG8_MMA(ai, bj, At, Bt) do { __builtin_amdgcn_s_setprio(1); _Pragma("unroll") for (int m = 0; m < 4; ++m) _Pragma("unroll") for (int n = 0; n < 2; ++n) _Pragma("unroll") for (int k = 0; k < 2; ++k) \
;         acc[ai][bj][m][n] = __builtin_amdgcn_mfma_f32_16x16x32_bf16(Bt[n][k], At[m][k], acc[ai][bj][m][n], 0, 0, 0); __builtin_amdgcn_s_setprio(0); } while (0)
; #define PG8_WAIT_V(n) asm volatile("s_waitcnt vmcnt(" #n ")" ::: "memory")
; #define PG8_WAIT_L(n) asm volatile("s_waitcnt lgkmcnt(" #n ")" ::: "memory")
; #define PG8_BAR __builtin_amdgcn_s_barrier()
; #define PG8_SCHED __builtin_amdgcn_sched_barrier(0)
; template <class Epi, class Sched, bool ALIGN_EPI = false, bool SP2 = false>
; __device__ __forceinline__ void gemm_phase(PG8_LAS unsigned char* lds, const Gemm g, const Sched& S, const Epi& E) {
;     ...
;             PG8_WAIT_V(8); PG8_WAIT_L(0); PG8_BAR; PG8_MMA(1, 0, At, B0); PG8_MMA(1, 1, At, B1); PG8_BAR; PG8_SCHED;
;             PG8_LDB(B0, 1, 0); PG8_LDB(B1, 1, 1); PG8_SCHED; PG8_LDA(At, 1, 0); PG8_STAGE(PG8_SA(0, 1), a2 + hstep, voffA);
;             PG8_WAIT_V(8); PG8_WAIT_L(0); PG8_BAR; PG8_MMA(0, 0, At, B0); PG8_MMA(0, 1, At, B1); PG8_BAR; PG8_SCHED;
	s_setprio 1
	s_waitcnt lgkmcnt(0)
	v_mfma_f32_16x16x32_bf16 v[58:61], v[140:143], v[194:197], v[58:61]
	v_mfma_f32_16x16x32_bf16 v[50:53], v[170:173], v[194:197], v[50:53]
	v_mfma_f32_16x16x32_bf16 v[42:45], v[140:143], v[202:205], v[42:45]
	v_mfma_f32_16x16x32_bf16 v[34:37], v[170:173], v[202:205], v[34:37]
	v_mfma_f32_16x16x32_bf16 v[26:29], v[140:143], v[214:217], v[26:29]
	v_mfma_f32_16x16x32_bf16 v[18:21], v[170:173], v[214:217], v[18:21]
	v_mfma_f32_16x16x32_bf16 v[10:13], v[140:143], v[222:225], v[10:13]
	v_mfma_f32_16x16x32_bf16 v[6:9], v[170:173], v[222:225], v[6:9]
	v_mfma_f32_16x16x32_bf16 v[58:61], v[166:169], v[198:201], v[58:61]
	v_mfma_f32_16x16x32_bf16 v[50:53], v[174:177], v[198:201], v[50:53]
	v_mfma_f32_16x16x32_bf16 v[42:45], v[166:169], v[210:213], v[42:45]
	v_mfma_f32_16x16x32_bf16 v[34:37], v[174:177], v[210:213], v[34:37]
	v_mfma_f32_16x16x32_bf16 v[26:29], v[166:169], v[218:221], v[26:29]
	v_mfma_f32_16x16x32_bf16 v[18:21], v[174:177], v[218:221], v[18:21]
	v_mfma_f32_16x16x32_bf16 v[10:13], v[166:169], v[238:241], v[10:13]
	v_mfma_f32_16x16x32_bf16 v[6:9], v[174:177], v[238:241], v[6:9]
	s_setprio 0
	s_setprio 1
	v_mfma_f32_16x16x32_bf16 v[62:65], v[178:181], v[194:197], v[62:65]
	v_mfma_f32_16x16x32_bf16 v[54:57], v[186:189], v[194:197], v[54:57]
	v_mfma_f32_16x16x32_bf16 v[46:49], v[178:181], v[202:205], v[46:49]
	v_mfma_f32_16x16x32_bf16 v[38:41], v[186:189], v[202:205], v[38:41]
	v_mfma_f32_16x16x32_bf16 v[30:33], v[178:181], v[214:217], v[30:33]
	v_mfma_f32_16x16x32_bf16 v[22:25], v[186:189], v[214:217], v[22:25]
	v_mfma_f32_16x16x32_bf16 v[14:17], v[178:181], v[222:225], v[14:17]
	v_mfma_f32_16x16x32_bf16 v[2:5], v[186:189], v[222:225], v[2:5]
	v_mfma_f32_16x16x32_bf16 v[62:65], v[182:185], v[198:201], v[62:65]
	v_mfma_f32_16x16x32_bf16 v[54:57], v[190:193], v[198:201], v[54:57]
	v_mfma_f32_16x16x32_bf16 v[46:49], v[182:185], v[210:213], v[46:49]
	v_mfma_f32_16x16x32_bf16 v[38:41], v[190:193], v[210:213], v[38:41]
	v_mfma_f32_16x16x32_bf16 v[30:33], v[182:185], v[218:221], v[30:33]
	v_mfma_f32_16x16x32_bf16 v[22:25], v[190:193], v[218:221], v[22:25]
	v_mfma_f32_16x16x32_bf16 v[14:17], v[182:185], v[238:241], v[14:17]
	v_mfma_f32_16x16x32_bf16 v[2:5], v[190:193], v[238:241], v[2:5]
	s_setprio 0
	s_barrier
	s_add_i32 s61, 0, 0x18000
	v_add_u32_e32 v146, s61, v149
	s_add_i32 s63, 0, 0x1c000
	ds_read_b128 v[140:143], v146
	ds_read_b128 v[166:169], v146 offset:1024
	ds_read_b128 v[170:173], v146 offset:2048
	ds_read_b128 v[174:177], v146 offset:3072
	v_add_u32_e32 v146, s63, v149
	ds_read_b128 v[178:181], v146
	ds_read_b128 v[182:185], v146 offset:1024
	ds_read_b128 v[186:189], v146 offset:2048
	ds_read_b128 v[190:193], v146 offset:3072
	s_add_u32 s70, s70, s12
	s_addc_u32 s71, s71, s13
	s_mov_b32 m0, s48
	v_lshl_add_u64 v[244:245], s[70:71], 0, v[134:135]
	ds_read_b128 v[194:197], v157 offset:32768
	ds_read_b128 v[198:201], v157 offset:33792
	ds_read_b128 v[202:205], v157 offset:34816
	ds_read_b128 v[210:213], v157 offset:35840
	ds_read_b128 v[214:217], v157 offset:36864
	ds_read_b128 v[218:221], v157 offset:37888
	ds_read_b128 v[222:225], v157 offset:38912
	ds_read_b128 v[238:241], v157 offset:39936
	global_load_lds_dwordx4 v[244:245], off
	v_lshl_add_u64 v[244:245], s[70:71], 0, v[132:133]
	s_mov_b32 m0, s49
	s_nop 0
	global_load_lds_dwordx4 v[244:245], off
	s_waitcnt vmcnt(8)
	s_waitcnt lgkmcnt(0)
	s_barrier
	s_setprio 1
	s_waitcnt lgkmcnt(0)
	v_mfma_f32_16x16x32_bf16 v[122:125], v[140:143], v[194:197], v[122:125]
	v_mfma_f32_16x16x32_bf16 v[114:117], v[170:173], v[194:197], v[114:117]
	v_mfma_f32_16x16x32_bf16 v[106:109], v[140:143], v[202:205], v[106:109]
	v_mfma_f32_16x16x32_bf16 v[98:101], v[170:173], v[202:205], v[98:101]
	v_mfma_f32_16x16x32_bf16 v[90:93], v[140:143], v[214:217], v[90:93]
	v_mfma_f32_16x16x32_bf16 v[82:85], v[170:173], v[214:217], v[82:85]
	v_mfma_f32_16x16x32_bf16 v[74:77], v[140:143], v[222:225], v[74:77]
	v_mfma_f32_16x16x32_bf16 v[66:69], v[170:173], v[222:225], v[66:69]
	v_mfma_f32_16x16x32_bf16 v[122:125], v[166:169], v[198:201], v[122:125]
	v_mfma_f32_16x16x32_bf16 v[114:117], v[174:177], v[198:201], v[114:117]
	v_mfma_f32_16x16x32_bf16 v[106:109], v[166:169], v[210:213], v[106:109]
	v_mfma_f32_16x16x32_bf16 v[98:101], v[174:177], v[210:213], v[98:101]
	v_mfma_f32_16x16x32_bf16 v[90:93], v[166:169], v[218:221], v[90:93]
	v_mfma_f32_16x16x32_bf16 v[82:85], v[174:177], v[218:221], v[82:85]
	v_mfma_f32_16x16x32_bf16 v[74:77], v[166:169], v[238:241], v[74:77]
	v_mfma_f32_16x16x32_bf16 v[66:69], v[174:177], v[238:241], v[66:69]
	s_setprio 0
	s_setprio 1
	v_mfma_f32_16x16x32_bf16 v[126:129], v[178:181], v[194:197], v[126:129]
	v_mfma_f32_16x16x32_bf16 v[118:121], v[186:189], v[194:197], v[118:121]
	v_mfma_f32_16x16x32_bf16 v[110:113], v[178:181], v[202:205], v[110:113]
	v_mfma_f32_16x16x32_bf16 v[102:105], v[186:189], v[202:205], v[102:105]
	v_mfma_f32_16x16x32_bf16 v[94:97], v[178:181], v[214:217], v[94:97]
	v_mfma_f32_16x16x32_bf16 v[86:89], v[186:189], v[214:217], v[86:89]
	v_mfma_f32_16x16x32_bf16 v[78:81], v[178:181], v[222:225], v[78:81]
	v_mfma_f32_16x16x32_bf16 v[70:73], v[186:189], v[222:225], v[70:73]
	v_mfma_f32_16x16x32_bf16 v[126:129], v[182:185], v[198:201], v[126:129]
	v_mfma_f32_16x16x32_bf16 v[118:121], v[190:193], v[198:201], v[118:121]
	v_mfma_f32_16x16x32_bf16 v[110:113], v[182:185], v[210:213], v[110:113]
	v_mfma_f32_16x16x32_bf16 v[102:105], v[190:193], v[210:213], v[102:105]
	v_mfma_f32_16x16x32_bf16 v[94:97], v[182:185], v[218:221], v[94:97]
	v_mfma_f32_16x16x32_bf16 v[86:89], v[190:193], v[218:221], v[86:89]
	v_mfma_f32_16x16x32_bf16 v[78:81], v[182:185], v[238:241], v[78:81]
	v_mfma_f32_16x16x32_bf16 v[70:73], v[190:193], v[238:241], v[70:73]
	s_setprio 0
	s_barrier
; #define PG8_STAGE(bufoff, gbase, voff) do { _Pragma("unroll") for (int _i = 0; _i < 2; ++_i) \
;         __builtin_amdgcn_global_load_lds((const unsigned*)((const char*)(gbase) + (voff)[_i]), (PG8_LAS unsigned*)(lds + (bufoff) + ldsw + _i * 8192), 16, 0, 0); } while (0)
; #define PG8_LDA(dst, b, h) do { _Pragma("unroll") for (int m = 0; m < 4; ++m) _Pragma("unroll") for (int k = 0; k < 2; ++k) dst[m][k] = *(const PG8_LAS bf16x8*)(lds + PG8_SA(b, h) + aoff + m * 2048 + k * 1024); } while (0)
; #define PG8_MMA(ai, bj, At, Bt) do { __builtin_amdgcn_s_setprio(1); _Pragma("unroll") for (int m = 0; m < 4; ++m) _Pragma("unroll") for (int n = 0; n < 2; ++n) _Pragma("unroll") for (int k = 0; k < 2; ++k) \
;         acc[ai][bj][m][n] = __builtin_amdgcn_mfma_f32_16x16x32_bf16(Bt[n][k], At[m][k], acc[ai][bj][m][n], 0, 0, 0); __builtin_amdgcn_s_setprio(0); } while (0)
; #define PG8_WAIT_V(n) asm volatile("s_waitcnt vmcnt(" #n ")" ::: "memory")
; #define PG8_WAIT_L(n) asm volatile("s_waitcnt lgkmcnt(" #n ")" ::: "memory")
; #define PG8_BAR __builtin_amdgcn_s_barrier()
; #define PG8_SCHED __builtin_amdgcn_sched_barrier(0)
; template <class Epi, class Sched, bool ALIGN_EPI = false, bool SP2 = false>
; __device__ __forceinline__ void gemm_phase(PG8_LAS unsigned char* lds, const Gemm g, const Sched& S, const Epi& E) {
;     ...
;             PG8_LDA(At, 1, 1); PG8_STAGE(PG8_SB(1, 0), b3, voffB); PG8_STAGE(PG8_SB(1, 1), b3 + hstep, voffB); PG8_STAGE(PG8_SA(1, 0), a3, voffA);
;             PG8_WAIT_V(8); PG8_WAIT_L(0); PG8_BAR; PG8_MMA(1, 0, At, B0); PG8_MMA(1, 1, At, B1); PG8_BAR; PG8_SCHED;
;     __device__ __forceinline__ void operator()(const f32x4 (&acc)[2][2][4][2], const Unit& u, int wr, int wc, int fr, int fq) const {
;     ...
;             for (int m = 0; m < 4; ++m) pp[ai][m] = *(const f32x4*)(rss + (size_t)(row0 + ai * 128 + m * 16) * 4);
	s_add_i32 s61, s61, s6
	v_lshl_add_u64 v[144:145], v[144:145], 0, s[22:23]
	s_mov_b32 m0, s61
	ds_read_b128 v[194:197], v157 offset:49152
	ds_read_b128 v[198:201], v157 offset:50176
	ds_read_b128 v[202:205], v157 offset:51200
	ds_read_b128 v[210:213], v157 offset:52224
	ds_read_b128 v[214:217], v157 offset:53248
	ds_read_b128 v[218:221], v157 offset:54272
	ds_read_b128 v[222:225], v157 offset:55296
	ds_read_b128 v[238:241], v157 offset:56320
	global_load_lds_dwordx4 v[144:145], off
	v_lshl_add_u64 v[144:145], v[150:151], 0, s[22:23]
	s_add_i32 m0, s61, 0x2000
	s_add_i32 s61, s63, s6
	global_load_lds_dwordx4 v[144:145], off
	v_lshl_add_u64 v[144:145], v[154:155], 0, s[22:23]
	s_mov_b32 m0, s61
	s_nop 0
	global_load_lds_dwordx4 v[144:145], off
	v_lshl_add_u64 v[144:145], v[206:207], 0, s[22:23]
	s_add_i32 m0, s61, 0x2000
	s_nop 0
	global_load_lds_dwordx4 v[144:145], off
	v_lshl_add_u64 v[144:145], v[226:227], 0, s[22:23]
	s_mov_b32 m0, s51
	s_nop 0
	global_load_lds_dwordx4 v[144:145], off
	v_lshl_add_u64 v[144:145], v[242:243], 0, s[22:23]
	s_mov_b32 m0, s52
	s_nop 0
	global_load_lds_dwordx4 v[144:145], off
	s_waitcnt vmcnt(8)
	s_waitcnt lgkmcnt(0)
	s_barrier
	s_setprio 1
	s_waitcnt lgkmcnt(0)
	v_mfma_f32_16x16x32_bf16 v[58:61], v[140:143], v[194:197], v[58:61]
	v_mfma_f32_16x16x32_bf16 v[50:53], v[170:173], v[194:197], v[50:53]
	v_mfma_f32_16x16x32_bf16 v[42:45], v[140:143], v[202:205], v[42:45]
	v_mfma_f32_16x16x32_bf16 v[34:37], v[170:173], v[202:205], v[34:37]
	v_mfma_f32_16x16x32_bf16 v[26:29], v[140:143], v[214:217], v[26:29]
	v_mfma_f32_16x16x32_bf16 v[18:21], v[170:173], v[214:217], v[18:21]
	v_mfma_f32_16x16x32_bf16 v[10:13], v[140:143], v[222:225], v[10:13]
	v_mfma_f32_16x16x32_bf16 v[6:9], v[170:173], v[222:225], v[6:9]
	v_mfma_f32_16x16x32_bf16 v[58:61], v[166:169], v[198:201], v[58:61]
	v_mfma_f32_16x16x32_bf16 v[50:53], v[174:177], v[198:201], v[50:53]
	v_mfma_f32_16x16x32_bf16 v[42:45], v[166:169], v[210:213], v[42:45]
	v_mfma_f32_16x16x32_bf16 v[34:37], v[174:177], v[210:213], v[34:37]
	v_mfma_f32_16x16x32_bf16 v[26:29], v[166:169], v[218:221], v[26:29]
	v_mfma_f32_16x16x32_bf16 v[18:21], v[174:177], v[218:221], v[18:21]
	v_mfma_f32_16x16x32_bf16 v[10:13], v[166:169], v[238:241], v[10:13]
	v_mfma_f32_16x16x32_bf16 v[6:9], v[174:177], v[238:241], v[6:9]
	s_setprio 0
	s_setprio 1
	v_mfma_f32_16x16x32_bf16 v[62:65], v[178:181], v[194:197], v[62:65]
	v_mfma_f32_16x16x32_bf16 v[54:57], v[186:189], v[194:197], v[54:57]
	v_mfma_f32_16x16x32_bf16 v[46:49], v[178:181], v[202:205], v[46:49]
	v_mfma_f32_16x16x32_bf16 v[38:41], v[186:189], v[202:205], v[38:41]
	v_mfma_f32_16x16x32_bf16 v[30:33], v[178:181], v[214:217], v[30:33]
	v_mfma_f32_16x16x32_bf16 v[22:25], v[186:189], v[214:217], v[22:25]
	v_mfma_f32_16x16x32_bf16 v[14:17], v[178:181], v[222:225], v[14:17]
	v_mfma_f32_16x16x32_bf16 v[2:5], v[186:189], v[222:225], v[2:5]
	v_mfma_f32_16x16x32_bf16 v[62:65], v[182:185], v[198:201], v[62:65]
	v_mfma_f32_16x16x32_bf16 v[54:57], v[190:193], v[198:201], v[54:57]
	v_mfma_f32_16x16x32_bf16 v[46:49], v[182:185], v[210:213], v[46:49]
	v_mfma_f32_16x16x32_bf16 v[38:41], v[190:193], v[210:213], v[38:41]
	v_mfma_f32_16x16x32_bf16 v[30:33], v[182:185], v[218:221], v[30:33]
	v_mfma_f32_16x16x32_bf16 v[22:25], v[190:193], v[218:221], v[22:25]
	v_mfma_f32_16x16x32_bf16 v[14:17], v[182:185], v[238:241], v[14:17]
	v_mfma_f32_16x16x32_bf16 v[2:5], v[190:193], v[238:241], v[2:5]
	s_setprio 0
	s_barrier
	s_sub_u32 s100, s50, 6
	s_cmp_eq_u32 s61, s100
	s_cbranch_scc0 .Lrs_gu2
	v_readlane_b32 s100, v250, 28
	v_readlane_b32 s101, v250, 29
	v_and_b32_e32 v255, 63, v158
	v_lshlrev_b32_e32 v255, 6, v255
	v_lshl_add_u32 v254, s58, 12, v255
	s_nop 2
	global_load_dword v254, v254, s[100:101]
.Lrs_gu2:
	s_add_u32 s68, s68, 0x100
	s_addc_u32 s69, s69, 0
	s_add_u32 s59, s59, 0x100
	s_addc_u32 s60, s60, 0
	s_cmp_ge_i32 s62, s50
	s_mov_b32 s61, s62
	s_cbranch_scc0 .LBB0_1191
	v_readlane_b32 s80, v250, 13
	v_readlane_b32 s62, v250, 20
	v_readlane_b32 s81, v250, 14
	s_mov_b32 s84, s62
	v_readlane_b32 s63, v250, 21
